# c16: c15 + k-step pairing also in the two rotating-accumulator K-loops (K/V and Q projections)
# speedup vs baseline: 1.0025x; 1.0025x over previous
.LBB0_1537:
	s_ashr_i32 s23, s22, 31
	s_lshl_b64 s[24:25], s[22:23], 20
	s_add_u32 s24, s41, s24
	s_addc_u32 s25, s42, s25
	s_and_b64 s[26:27], s[4:5], exec
	s_cselect_b32 s7, s25, s35
	s_cselect_b32 s23, s24, s34
	s_ashr_i32 s21, s20, 31
	s_lshl_b64 s[26:27], s[20:21], 20
	s_add_u32 s26, s43, s26
	s_addc_u32 s27, s46, s27
	s_and_b64 s[36:37], s[4:5], exec
	s_cselect_b32 s21, s27, s31
	s_cselect_b32 s29, s26, s30
	s_add_u32 s79, s30, 0x100
	s_addc_u32 s80, s31, 0
	s_add_u32 s30, s34, 0x80080
	s_addc_u32 s31, s35, 0
	s_add_u32 s81, s34, 0x100
	s_addc_u32 s82, s35, 0
	s_mov_b32 s83, -2
	s_waitcnt vmcnt(25)
	s_waitcnt vmcnt(24)
	s_waitcnt vmcnt(4)
	s_waitcnt vmcnt(14)
	s_waitcnt vmcnt(13)
	s_waitcnt vmcnt(12)
	s_waitcnt vmcnt(2)
	s_waitcnt vmcnt(10)
	s_waitcnt vmcnt(9)
	s_waitcnt vmcnt(8)
	s_waitcnt vmcnt(7)
	s_waitcnt vmcnt(6)
	s_waitcnt vmcnt(5)
	s_waitcnt vmcnt(4)
	s_waitcnt vmcnt(3)
	s_waitcnt vmcnt(2)
	s_waitcnt vmcnt(1)
	s_waitcnt vmcnt(0)
	ds_read_b128 v[46:49], v182
	ds_read_b128 v[54:57], v182 offset:1024
	ds_read_b128 v[58:61], v182 offset:2048
	ds_read_b128 v[62:65], v182 offset:3072
	ds_read_b128 v[146:149], v183
	ds_read_b128 v[150:153], v183 offset:1024
	ds_read_b128 v[154:157], v183 offset:2048
	ds_read_b128 v[158:161], v183 offset:3072
	s_cmp_eq_u32 s83, 28
	s_cselect_b32 s35, s21, s80
	s_cselect_b32 s34, s29, s79
	s_cselect_b32 s37, s7, s82
	s_cselect_b32 s36, s23, s81
	ds_read_b128 v[170:173], v184
	ds_read_b128 v[188:191], v184 offset:1024
	ds_read_b128 v[192:195], v184 offset:2048
	ds_read_b128 v[196:199], v184 offset:3072
	ds_read_b128 v[200:203], v184 offset:4096
	ds_read_b128 v[204:207], v184 offset:5120
	ds_read_b128 v[208:211], v184 offset:6144
	ds_read_b128 v[212:215], v184 offset:7168
	s_add_u32 s86, s30, 0xfff80000
	s_addc_u32 s87, s31, -1
	s_mov_b32 s92, m0
	s_mov_b32 m0, s73
	s_nop 0
	global_load_lds_dwordx4 v176, s[86:87]
	s_mov_b32 m0, s92
	s_nop 0
	s_mov_b32 s92, m0
	s_mov_b32 m0, s75
	s_nop 0
	global_load_lds_dwordx4 v178, s[86:87]
	s_mov_b32 m0, s92
	s_mov_b32 s86, m0
	s_mov_b32 m0, s74
	s_nop 0
	global_load_lds_dwordx4 v176, s[30:31]
	s_mov_b32 m0, s86
	s_nop 0
	s_mov_b32 s86, m0
	s_mov_b32 m0, s76
	s_nop 0
	global_load_lds_dwordx4 v178, s[30:31]
	s_mov_b32 m0, s86
	s_waitcnt vmcnt(8)
	s_waitcnt lgkmcnt(0)
	s_barrier
	s_setprio 1
	s_waitcnt lgkmcnt(7)
	v_mfma_f32_16x16x32_bf16 v[142:145], v[46:49], v[170:173], 0
	v_mfma_f32_16x16x32_bf16 v[142:145], v[54:57], v[188:191], v[142:145]
	s_waitcnt lgkmcnt(5)
	v_mfma_f32_16x16x32_bf16 v[138:141], v[58:61], v[170:173], 0
	v_mfma_f32_16x16x32_bf16 v[138:141], v[62:65], v[188:191], v[138:141]
	s_waitcnt lgkmcnt(3)
	v_mfma_f32_16x16x32_bf16 v[126:129], v[46:49], v[192:195], 0
	v_mfma_f32_16x16x32_bf16 v[126:129], v[54:57], v[196:199], v[126:129]
	s_waitcnt lgkmcnt(1)
	v_mfma_f32_16x16x32_bf16 v[122:125], v[58:61], v[192:195], 0
	v_mfma_f32_16x16x32_bf16 v[122:125], v[62:65], v[196:199], v[122:125]
	v_mfma_f32_16x16x32_bf16 v[110:113], v[46:49], v[200:203], 0
	v_mfma_f32_16x16x32_bf16 v[110:113], v[54:57], v[204:207], v[110:113]
	v_mfma_f32_16x16x32_bf16 v[106:109], v[58:61], v[200:203], 0
	v_mfma_f32_16x16x32_bf16 v[106:109], v[62:65], v[204:207], v[106:109]
	v_mfma_f32_16x16x32_bf16 v[94:97], v[46:49], v[208:211], 0
	v_mfma_f32_16x16x32_bf16 v[94:97], v[54:57], v[212:215], v[94:97]
	s_waitcnt lgkmcnt(0)
	v_mfma_f32_16x16x32_bf16 v[90:93], v[58:61], v[208:211], 0
	v_mfma_f32_16x16x32_bf16 v[90:93], v[62:65], v[212:215], v[90:93]
	s_setprio 0
	s_setprio 1
	v_mfma_f32_16x16x32_bf16 v[134:137], v[146:149], v[170:173], 0
	v_mfma_f32_16x16x32_bf16 v[134:137], v[150:153], v[188:191], v[134:137]
	v_mfma_f32_16x16x32_bf16 v[130:133], v[154:157], v[170:173], 0
	v_mfma_f32_16x16x32_bf16 v[130:133], v[158:161], v[188:191], v[130:133]
	v_mfma_f32_16x16x32_bf16 v[118:121], v[146:149], v[192:195], 0
	v_mfma_f32_16x16x32_bf16 v[118:121], v[150:153], v[196:199], v[118:121]
	v_mfma_f32_16x16x32_bf16 v[114:117], v[154:157], v[192:195], 0
	v_mfma_f32_16x16x32_bf16 v[114:117], v[158:161], v[196:199], v[114:117]
	v_mfma_f32_16x16x32_bf16 v[102:105], v[146:149], v[200:203], 0
	v_mfma_f32_16x16x32_bf16 v[102:105], v[150:153], v[204:207], v[102:105]
	v_mfma_f32_16x16x32_bf16 v[98:101], v[154:157], v[200:203], 0
	v_mfma_f32_16x16x32_bf16 v[98:101], v[158:161], v[204:207], v[98:101]
	v_mfma_f32_16x16x32_bf16 v[86:89], v[146:149], v[208:211], 0
	v_mfma_f32_16x16x32_bf16 v[86:89], v[150:153], v[212:215], v[86:89]
	s_setprio 2
	s_barrier
	v_mfma_f32_16x16x32_bf16 v[82:85], v[154:157], v[208:211], 0
	v_mfma_f32_16x16x32_bf16 v[82:85], v[158:161], v[212:215], v[82:85]
	s_setprio 0
	ds_read_b128 v[170:173], v184 offset:16384
	ds_read_b128 v[188:191], v184 offset:17408
	ds_read_b128 v[192:195], v184 offset:18432
	ds_read_b128 v[196:199], v184 offset:19456
	ds_read_b128 v[200:203], v184 offset:20480
	ds_read_b128 v[204:207], v184 offset:21504
	ds_read_b128 v[208:211], v184 offset:22528
	ds_read_b128 v[212:215], v184 offset:23552
	s_mov_b32 s86, m0
	s_mov_b32 m0, s49
	s_nop 0
	global_load_lds_dwordx4 v177, s[34:35]
	s_mov_b32 m0, s86
	s_nop 0
	s_mov_b32 s86, m0
	s_mov_b32 m0, s56
	s_nop 0
	global_load_lds_dwordx4 v179, s[34:35]
	s_mov_b32 m0, s86
	s_add_u32 s86, s34, 0x80000
	s_addc_u32 s87, s35, 0
	s_mov_b32 s92, m0
	s_mov_b32 m0, s57
	s_nop 0
	global_load_lds_dwordx4 v177, s[86:87]
	s_mov_b32 m0, s92
	s_nop 0
	s_mov_b32 s92, m0
	s_mov_b32 m0, s58
	s_nop 0
	global_load_lds_dwordx4 v179, s[86:87]
	s_mov_b32 m0, s92
	s_waitcnt vmcnt(4)
	s_waitcnt lgkmcnt(0)
	s_barrier
	s_setprio 1
	s_waitcnt lgkmcnt(7)
	v_mfma_f32_16x16x32_bf16 v[78:81], v[46:49], v[170:173], 0
	v_mfma_f32_16x16x32_bf16 v[78:81], v[54:57], v[188:191], v[78:81]
	s_waitcnt lgkmcnt(5)
	v_mfma_f32_16x16x32_bf16 v[74:77], v[58:61], v[170:173], 0
	v_mfma_f32_16x16x32_bf16 v[74:77], v[62:65], v[188:191], v[74:77]
	s_waitcnt lgkmcnt(3)
	v_mfma_f32_16x16x32_bf16 v[50:53], v[46:49], v[192:195], 0
	v_mfma_f32_16x16x32_bf16 v[50:53], v[54:57], v[196:199], v[50:53]
	s_waitcnt lgkmcnt(1)
	v_mfma_f32_16x16x32_bf16 v[42:45], v[58:61], v[192:195], 0
	v_mfma_f32_16x16x32_bf16 v[42:45], v[62:65], v[196:199], v[42:45]
	v_mfma_f32_16x16x32_bf16 v[30:33], v[46:49], v[200:203], 0
	v_mfma_f32_16x16x32_bf16 v[30:33], v[54:57], v[204:207], v[30:33]
	v_mfma_f32_16x16x32_bf16 v[26:29], v[58:61], v[200:203], 0
	v_mfma_f32_16x16x32_bf16 v[26:29], v[62:65], v[204:207], v[26:29]
	v_mfma_f32_16x16x32_bf16 v[14:17], v[46:49], v[208:211], 0
	v_mfma_f32_16x16x32_bf16 v[14:17], v[54:57], v[212:215], v[14:17]
	s_waitcnt lgkmcnt(0)
	v_mfma_f32_16x16x32_bf16 v[10:13], v[58:61], v[208:211], 0
	v_mfma_f32_16x16x32_bf16 v[10:13], v[62:65], v[212:215], v[10:13]
	s_setprio 0
	s_setprio 1
	v_mfma_f32_16x16x32_bf16 v[38:41], v[146:149], v[192:195], 0
	v_mfma_f32_16x16x32_bf16 v[38:41], v[150:153], v[196:199], v[38:41]
	v_mfma_f32_16x16x32_bf16 v[34:37], v[154:157], v[192:195], 0
	v_mfma_f32_16x16x32_bf16 v[34:37], v[158:161], v[196:199], v[34:37]
	v_mfma_f32_16x16x32_bf16 v[22:25], v[146:149], v[200:203], 0
	v_mfma_f32_16x16x32_bf16 v[22:25], v[150:153], v[204:207], v[22:25]
	v_mfma_f32_16x16x32_bf16 v[18:21], v[154:157], v[200:203], 0
	v_mfma_f32_16x16x32_bf16 v[18:21], v[158:161], v[204:207], v[18:21]
	v_mfma_f32_16x16x32_bf16 v[6:9], v[146:149], v[208:211], 0
	v_mfma_f32_16x16x32_bf16 v[6:9], v[150:153], v[212:215], v[6:9]
	v_mfma_f32_16x16x32_bf16 v[2:5], v[154:157], v[208:211], 0
	v_mfma_f32_16x16x32_bf16 v[2:5], v[158:161], v[212:215], v[2:5]
	v_mfma_f32_16x16x32_bf16 v[46:49], v[146:149], v[170:173], 0
	v_mfma_f32_16x16x32_bf16 v[46:49], v[150:153], v[188:191], v[46:49]
	s_setprio 2
	s_barrier
	v_mfma_f32_16x16x32_bf16 v[54:57], v[154:157], v[170:173], 0
	v_mfma_f32_16x16x32_bf16 v[54:57], v[158:161], v[188:191], v[54:57]
	s_setprio 0
	ds_read_b128 v[58:61], v185
	ds_read_b128 v[62:65], v185 offset:1024
	ds_read_b128 v[66:69], v185 offset:2048
	ds_read_b128 v[70:73], v185 offset:3072
	ds_read_b128 v[146:149], v186
	ds_read_b128 v[150:153], v186 offset:1024
	ds_read_b128 v[154:157], v186 offset:2048
	ds_read_b128 v[158:161], v186 offset:3072
	ds_read_b128 v[170:173], v184 offset:32768
	ds_read_b128 v[188:191], v184 offset:33792
	ds_read_b128 v[192:195], v184 offset:34816
	ds_read_b128 v[196:199], v184 offset:35840
	ds_read_b128 v[200:203], v184 offset:36864
	ds_read_b128 v[204:207], v184 offset:37888
	ds_read_b128 v[208:211], v184 offset:38912
	ds_read_b128 v[212:215], v184 offset:39936
	s_mov_b32 s86, m0
	s_mov_b32 m0, s48
	s_nop 0
	global_load_lds_dwordx4 v176, s[36:37]
	s_mov_b32 m0, s86
	s_nop 0
	s_mov_b32 s86, m0
	s_mov_b32 m0, s59
	s_nop 0
	global_load_lds_dwordx4 v178, s[36:37]
	s_mov_b32 m0, s86
	s_add_u32 s36, s36, 0x80000
	s_addc_u32 s37, s37, 0
	s_mov_b32 s86, m0
	s_mov_b32 m0, s62
	s_nop 0
	global_load_lds_dwordx4 v176, s[36:37]
	s_mov_b32 m0, s86
	s_nop 0
	s_mov_b32 s86, m0
	s_mov_b32 m0, s63
	s_nop 0
	global_load_lds_dwordx4 v178, s[36:37]
	s_mov_b32 m0, s86
	s_waitcnt vmcnt(8)
	s_waitcnt lgkmcnt(0)
	s_barrier
	s_setprio 1
	s_waitcnt lgkmcnt(7)
	v_mfma_f32_16x16x32_bf16 v[142:145], v[58:61], v[170:173], v[142:145]
	v_mfma_f32_16x16x32_bf16 v[142:145], v[62:65], v[188:191], v[142:145]
	s_waitcnt lgkmcnt(5)
	v_mfma_f32_16x16x32_bf16 v[138:141], v[66:69], v[170:173], v[138:141]
	v_mfma_f32_16x16x32_bf16 v[138:141], v[70:73], v[188:191], v[138:141]
	s_waitcnt lgkmcnt(3)
	v_mfma_f32_16x16x32_bf16 v[126:129], v[58:61], v[192:195], v[126:129]
	v_mfma_f32_16x16x32_bf16 v[126:129], v[62:65], v[196:199], v[126:129]
	s_waitcnt lgkmcnt(1)
	v_mfma_f32_16x16x32_bf16 v[122:125], v[66:69], v[192:195], v[122:125]
	v_mfma_f32_16x16x32_bf16 v[122:125], v[70:73], v[196:199], v[122:125]
	v_mfma_f32_16x16x32_bf16 v[110:113], v[58:61], v[200:203], v[110:113]
	v_mfma_f32_16x16x32_bf16 v[110:113], v[62:65], v[204:207], v[110:113]
	v_mfma_f32_16x16x32_bf16 v[106:109], v[66:69], v[200:203], v[106:109]
	v_mfma_f32_16x16x32_bf16 v[106:109], v[70:73], v[204:207], v[106:109]
	v_mfma_f32_16x16x32_bf16 v[94:97], v[58:61], v[208:211], v[94:97]
	v_mfma_f32_16x16x32_bf16 v[94:97], v[62:65], v[212:215], v[94:97]
	s_waitcnt lgkmcnt(0)
	v_mfma_f32_16x16x32_bf16 v[90:93], v[66:69], v[208:211], v[90:93]
	v_mfma_f32_16x16x32_bf16 v[90:93], v[70:73], v[212:215], v[90:93]
	s_setprio 0
	s_setprio 1
	v_mfma_f32_16x16x32_bf16 v[134:137], v[146:149], v[170:173], v[134:137]
	v_mfma_f32_16x16x32_bf16 v[134:137], v[150:153], v[188:191], v[134:137]
	v_mfma_f32_16x16x32_bf16 v[130:133], v[154:157], v[170:173], v[130:133]
	v_mfma_f32_16x16x32_bf16 v[130:133], v[158:161], v[188:191], v[130:133]
	v_mfma_f32_16x16x32_bf16 v[118:121], v[146:149], v[192:195], v[118:121]
	v_mfma_f32_16x16x32_bf16 v[118:121], v[150:153], v[196:199], v[118:121]
	v_mfma_f32_16x16x32_bf16 v[114:117], v[154:157], v[192:195], v[114:117]
	v_mfma_f32_16x16x32_bf16 v[114:117], v[158:161], v[196:199], v[114:117]
	v_mfma_f32_16x16x32_bf16 v[102:105], v[146:149], v[200:203], v[102:105]
	v_mfma_f32_16x16x32_bf16 v[102:105], v[150:153], v[204:207], v[102:105]
	v_mfma_f32_16x16x32_bf16 v[98:101], v[154:157], v[200:203], v[98:101]
	v_mfma_f32_16x16x32_bf16 v[98:101], v[158:161], v[204:207], v[98:101]
	v_mfma_f32_16x16x32_bf16 v[86:89], v[146:149], v[208:211], v[86:89]
	v_mfma_f32_16x16x32_bf16 v[86:89], v[150:153], v[212:215], v[86:89]
	s_setprio 2
	s_barrier
	v_mfma_f32_16x16x32_bf16 v[82:85], v[154:157], v[208:211], v[82:85]
	v_mfma_f32_16x16x32_bf16 v[82:85], v[158:161], v[212:215], v[82:85]
	s_setprio 0
	ds_read_b128 v[170:173], v184 offset:49152
	ds_read_b128 v[188:191], v184 offset:50176
	ds_read_b128 v[192:195], v184 offset:51200
	ds_read_b128 v[196:199], v184 offset:52224
	ds_read_b128 v[200:203], v184 offset:53248
	ds_read_b128 v[204:207], v184 offset:54272
	ds_read_b128 v[208:211], v184 offset:55296
	ds_read_b128 v[212:215], v184 offset:56320
	s_add_u32 s36, s34, 0x80
	s_addc_u32 s37, s35, 0
	s_mov_b32 s86, m0
	s_mov_b32 m0, s64
	s_nop 0
	global_load_lds_dwordx4 v177, s[36:37]
	s_mov_b32 m0, s86
	s_add_u32 s34, s34, 0x80080
	s_mov_b32 s86, m0
	s_mov_b32 m0, s65
	s_nop 0
	global_load_lds_dwordx4 v179, s[36:37]
	s_mov_b32 m0, s86
	s_addc_u32 s35, s35, 0
	s_mov_b32 s36, m0
	s_mov_b32 m0, s66
	s_nop 0
	global_load_lds_dwordx4 v177, s[34:35]
	s_mov_b32 m0, s36
	s_nop 0
	s_mov_b32 s36, m0
	s_mov_b32 m0, s67
	s_nop 0
	global_load_lds_dwordx4 v179, s[34:35]
	s_mov_b32 m0, s36
	s_waitcnt vmcnt(4)
	s_waitcnt lgkmcnt(0)
	s_barrier
	s_setprio 1
	s_waitcnt lgkmcnt(7)
	v_mfma_f32_16x16x32_bf16 v[78:81], v[58:61], v[170:173], v[78:81]
	v_mfma_f32_16x16x32_bf16 v[78:81], v[62:65], v[188:191], v[78:81]
	s_waitcnt lgkmcnt(5)
	v_mfma_f32_16x16x32_bf16 v[74:77], v[66:69], v[170:173], v[74:77]
	v_mfma_f32_16x16x32_bf16 v[74:77], v[70:73], v[188:191], v[74:77]
	s_waitcnt lgkmcnt(3)
	v_mfma_f32_16x16x32_bf16 v[50:53], v[58:61], v[192:195], v[50:53]
	v_mfma_f32_16x16x32_bf16 v[50:53], v[62:65], v[196:199], v[50:53]
	s_waitcnt lgkmcnt(1)
	v_mfma_f32_16x16x32_bf16 v[42:45], v[66:69], v[192:195], v[42:45]
	v_mfma_f32_16x16x32_bf16 v[42:45], v[70:73], v[196:199], v[42:45]
	v_mfma_f32_16x16x32_bf16 v[30:33], v[58:61], v[200:203], v[30:33]
	v_mfma_f32_16x16x32_bf16 v[30:33], v[62:65], v[204:207], v[30:33]
	v_mfma_f32_16x16x32_bf16 v[26:29], v[66:69], v[200:203], v[26:29]
	v_mfma_f32_16x16x32_bf16 v[26:29], v[70:73], v[204:207], v[26:29]
	v_mfma_f32_16x16x32_bf16 v[14:17], v[58:61], v[208:211], v[14:17]
	v_mfma_f32_16x16x32_bf16 v[14:17], v[62:65], v[212:215], v[14:17]
	s_waitcnt lgkmcnt(0)
	v_mfma_f32_16x16x32_bf16 v[10:13], v[66:69], v[208:211], v[10:13]
	v_mfma_f32_16x16x32_bf16 v[10:13], v[70:73], v[212:215], v[10:13]
	s_setprio 0
	s_setprio 1
	v_mfma_f32_16x16x32_bf16 v[46:49], v[146:149], v[170:173], v[46:49]
	v_mfma_f32_16x16x32_bf16 v[70:73], v[150:153], v[188:191], v[46:49]
	v_mfma_f32_16x16x32_bf16 v[46:49], v[154:157], v[170:173], v[54:57]
	v_mfma_f32_16x16x32_bf16 v[66:69], v[158:161], v[188:191], v[46:49]
	v_mfma_f32_16x16x32_bf16 v[38:41], v[146:149], v[192:195], v[38:41]
	v_mfma_f32_16x16x32_bf16 v[38:41], v[150:153], v[196:199], v[38:41]
	v_mfma_f32_16x16x32_bf16 v[34:37], v[154:157], v[192:195], v[34:37]
	v_mfma_f32_16x16x32_bf16 v[34:37], v[158:161], v[196:199], v[34:37]
	v_mfma_f32_16x16x32_bf16 v[22:25], v[146:149], v[200:203], v[22:25]
	v_mfma_f32_16x16x32_bf16 v[22:25], v[150:153], v[204:207], v[22:25]
	v_mfma_f32_16x16x32_bf16 v[18:21], v[154:157], v[200:203], v[18:21]
	v_mfma_f32_16x16x32_bf16 v[18:21], v[158:161], v[204:207], v[18:21]
	v_mfma_f32_16x16x32_bf16 v[6:9], v[146:149], v[208:211], v[6:9]
	v_mfma_f32_16x16x32_bf16 v[6:9], v[150:153], v[212:215], v[6:9]
	s_setprio 2
	s_barrier
	v_mfma_f32_16x16x32_bf16 v[2:5], v[154:157], v[208:211], v[2:5]
	v_mfma_f32_16x16x32_bf16 v[2:5], v[158:161], v[212:215], v[2:5]
	s_setprio 0
	s_add_i32 s83, s83, 2
	s_add_u32 s79, s79, 0x100
	s_addc_u32 s80, s80, 0
	s_add_u32 s30, s30, 0x100
	s_addc_u32 s31, s31, 0
	s_add_u32 s81, s81, 0x100
	s_addc_u32 s82, s82, 0
	s_cmp_gt_u32 s83, 29
	.p2align 6
.LBB0_1538:
	ds_read_b128 v[46:49], v182
	ds_read_b128 v[54:57], v182 offset:1024
	ds_read_b128 v[58:61], v182 offset:2048
	ds_read_b128 v[62:65], v182 offset:3072
	ds_read_b128 v[146:149], v183
	ds_read_b128 v[150:153], v183 offset:1024
	ds_read_b128 v[154:157], v183 offset:2048
	ds_read_b128 v[158:161], v183 offset:3072
	s_cmp_eq_u32 s83, 28
	s_cselect_b32 s35, s21, s80
	s_cselect_b32 s34, s29, s79
	s_cselect_b32 s37, s7, s82
	s_cselect_b32 s36, s23, s81
	ds_read_b128 v[170:173], v184
	ds_read_b128 v[188:191], v184 offset:1024
	ds_read_b128 v[192:195], v184 offset:2048
	ds_read_b128 v[196:199], v184 offset:3072
	ds_read_b128 v[200:203], v184 offset:4096
	ds_read_b128 v[204:207], v184 offset:5120
	ds_read_b128 v[208:211], v184 offset:6144
	ds_read_b128 v[212:215], v184 offset:7168
	s_add_u32 s86, s30, 0xfff80000
	s_addc_u32 s87, s31, -1
	s_mov_b32 s92, m0
	s_mov_b32 m0, s73
	s_nop 0
	global_load_lds_dwordx4 v176, s[86:87]
	s_mov_b32 m0, s92
	s_nop 0
	s_mov_b32 s92, m0
	s_mov_b32 m0, s75
	s_nop 0
	global_load_lds_dwordx4 v178, s[86:87]
	s_mov_b32 m0, s92
	s_mov_b32 s86, m0
	s_mov_b32 m0, s74
	s_nop 0
	global_load_lds_dwordx4 v176, s[30:31]
	s_mov_b32 m0, s86
	s_nop 0
	s_mov_b32 s86, m0
	s_mov_b32 m0, s76
	s_nop 0
	global_load_lds_dwordx4 v178, s[30:31]
	s_mov_b32 m0, s86
	s_waitcnt vmcnt(8)
	s_waitcnt lgkmcnt(0)
	s_barrier
	s_setprio 1
	s_waitcnt lgkmcnt(7)
	v_mfma_f32_16x16x32_bf16 v[142:145], v[46:49], v[170:173], v[142:145]
	v_mfma_f32_16x16x32_bf16 v[142:145], v[54:57], v[188:191], v[142:145]
	s_waitcnt lgkmcnt(5)
	v_mfma_f32_16x16x32_bf16 v[138:141], v[58:61], v[170:173], v[138:141]
	v_mfma_f32_16x16x32_bf16 v[138:141], v[62:65], v[188:191], v[138:141]
	s_waitcnt lgkmcnt(3)
	v_mfma_f32_16x16x32_bf16 v[126:129], v[46:49], v[192:195], v[126:129]
	v_mfma_f32_16x16x32_bf16 v[126:129], v[54:57], v[196:199], v[126:129]
	s_waitcnt lgkmcnt(1)
	v_mfma_f32_16x16x32_bf16 v[122:125], v[58:61], v[192:195], v[122:125]
	v_mfma_f32_16x16x32_bf16 v[122:125], v[62:65], v[196:199], v[122:125]
	v_mfma_f32_16x16x32_bf16 v[110:113], v[46:49], v[200:203], v[110:113]
	v_mfma_f32_16x16x32_bf16 v[110:113], v[54:57], v[204:207], v[110:113]
	v_mfma_f32_16x16x32_bf16 v[106:109], v[58:61], v[200:203], v[106:109]
	v_mfma_f32_16x16x32_bf16 v[106:109], v[62:65], v[204:207], v[106:109]
	v_mfma_f32_16x16x32_bf16 v[94:97], v[46:49], v[208:211], v[94:97]
	v_mfma_f32_16x16x32_bf16 v[94:97], v[54:57], v[212:215], v[94:97]
	s_waitcnt lgkmcnt(0)
	v_mfma_f32_16x16x32_bf16 v[90:93], v[58:61], v[208:211], v[90:93]
	v_mfma_f32_16x16x32_bf16 v[90:93], v[62:65], v[212:215], v[90:93]
	s_setprio 0
	s_setprio 1
	v_mfma_f32_16x16x32_bf16 v[134:137], v[146:149], v[170:173], v[134:137]
	v_mfma_f32_16x16x32_bf16 v[134:137], v[150:153], v[188:191], v[134:137]
	v_mfma_f32_16x16x32_bf16 v[130:133], v[154:157], v[170:173], v[130:133]
	v_mfma_f32_16x16x32_bf16 v[130:133], v[158:161], v[188:191], v[130:133]
	v_mfma_f32_16x16x32_bf16 v[118:121], v[146:149], v[192:195], v[118:121]
	v_mfma_f32_16x16x32_bf16 v[118:121], v[150:153], v[196:199], v[118:121]
	v_mfma_f32_16x16x32_bf16 v[114:117], v[154:157], v[192:195], v[114:117]
	v_mfma_f32_16x16x32_bf16 v[114:117], v[158:161], v[196:199], v[114:117]
	v_mfma_f32_16x16x32_bf16 v[102:105], v[146:149], v[200:203], v[102:105]
	v_mfma_f32_16x16x32_bf16 v[102:105], v[150:153], v[204:207], v[102:105]
	v_mfma_f32_16x16x32_bf16 v[98:101], v[154:157], v[200:203], v[98:101]
	v_mfma_f32_16x16x32_bf16 v[98:101], v[158:161], v[204:207], v[98:101]
	v_mfma_f32_16x16x32_bf16 v[86:89], v[146:149], v[208:211], v[86:89]
	v_mfma_f32_16x16x32_bf16 v[86:89], v[150:153], v[212:215], v[86:89]
	s_setprio 2
	s_barrier
	v_mfma_f32_16x16x32_bf16 v[82:85], v[154:157], v[208:211], v[82:85]
	v_mfma_f32_16x16x32_bf16 v[82:85], v[158:161], v[212:215], v[82:85]
	s_setprio 0
	ds_read_b128 v[170:173], v184 offset:16384
	ds_read_b128 v[188:191], v184 offset:17408
	ds_read_b128 v[192:195], v184 offset:18432
	ds_read_b128 v[196:199], v184 offset:19456
	ds_read_b128 v[200:203], v184 offset:20480
	ds_read_b128 v[204:207], v184 offset:21504
	ds_read_b128 v[208:211], v184 offset:22528
	ds_read_b128 v[212:215], v184 offset:23552
	s_mov_b32 s86, m0
	s_mov_b32 m0, s49
	s_nop 0
	global_load_lds_dwordx4 v177, s[34:35]
	s_mov_b32 m0, s86
	s_nop 0
	s_mov_b32 s86, m0
	s_mov_b32 m0, s56
	s_nop 0
	global_load_lds_dwordx4 v179, s[34:35]
	s_mov_b32 m0, s86
	s_add_u32 s86, s34, 0x80000
	s_addc_u32 s87, s35, 0
	s_mov_b32 s92, m0
	s_mov_b32 m0, s57
	s_nop 0
	global_load_lds_dwordx4 v177, s[86:87]
	s_mov_b32 m0, s92
	s_nop 0
	s_mov_b32 s92, m0
	s_mov_b32 m0, s58
	s_nop 0
	global_load_lds_dwordx4 v179, s[86:87]
	s_mov_b32 m0, s92
	s_waitcnt vmcnt(4)
	s_waitcnt lgkmcnt(0)
	s_barrier
	s_setprio 1
	s_waitcnt lgkmcnt(7)
	v_mfma_f32_16x16x32_bf16 v[78:81], v[46:49], v[170:173], v[78:81]
	v_mfma_f32_16x16x32_bf16 v[78:81], v[54:57], v[188:191], v[78:81]
	s_waitcnt lgkmcnt(5)
	v_mfma_f32_16x16x32_bf16 v[74:77], v[58:61], v[170:173], v[74:77]
	v_mfma_f32_16x16x32_bf16 v[74:77], v[62:65], v[188:191], v[74:77]
	s_waitcnt lgkmcnt(3)
	v_mfma_f32_16x16x32_bf16 v[50:53], v[46:49], v[192:195], v[50:53]
	v_mfma_f32_16x16x32_bf16 v[50:53], v[54:57], v[196:199], v[50:53]
	s_waitcnt lgkmcnt(1)
	v_mfma_f32_16x16x32_bf16 v[42:45], v[58:61], v[192:195], v[42:45]
	v_mfma_f32_16x16x32_bf16 v[42:45], v[62:65], v[196:199], v[42:45]
	v_mfma_f32_16x16x32_bf16 v[30:33], v[46:49], v[200:203], v[30:33]
	v_mfma_f32_16x16x32_bf16 v[30:33], v[54:57], v[204:207], v[30:33]
	v_mfma_f32_16x16x32_bf16 v[26:29], v[58:61], v[200:203], v[26:29]
	v_mfma_f32_16x16x32_bf16 v[26:29], v[62:65], v[204:207], v[26:29]
	v_mfma_f32_16x16x32_bf16 v[14:17], v[46:49], v[208:211], v[14:17]
	v_mfma_f32_16x16x32_bf16 v[14:17], v[54:57], v[212:215], v[14:17]
	s_waitcnt lgkmcnt(0)
	v_mfma_f32_16x16x32_bf16 v[10:13], v[58:61], v[208:211], v[10:13]
	v_mfma_f32_16x16x32_bf16 v[10:13], v[62:65], v[212:215], v[10:13]
	s_setprio 0
	s_setprio 1
	v_mfma_f32_16x16x32_bf16 v[38:41], v[146:149], v[192:195], v[38:41]
	v_mfma_f32_16x16x32_bf16 v[38:41], v[150:153], v[196:199], v[38:41]
	v_mfma_f32_16x16x32_bf16 v[34:37], v[154:157], v[192:195], v[34:37]
	v_mfma_f32_16x16x32_bf16 v[34:37], v[158:161], v[196:199], v[34:37]
	v_mfma_f32_16x16x32_bf16 v[22:25], v[146:149], v[200:203], v[22:25]
	v_mfma_f32_16x16x32_bf16 v[22:25], v[150:153], v[204:207], v[22:25]
	v_mfma_f32_16x16x32_bf16 v[18:21], v[154:157], v[200:203], v[18:21]
	v_mfma_f32_16x16x32_bf16 v[18:21], v[158:161], v[204:207], v[18:21]
	v_mfma_f32_16x16x32_bf16 v[6:9], v[146:149], v[208:211], v[6:9]
	v_mfma_f32_16x16x32_bf16 v[6:9], v[150:153], v[212:215], v[6:9]
	v_mfma_f32_16x16x32_bf16 v[2:5], v[154:157], v[208:211], v[2:5]
	v_mfma_f32_16x16x32_bf16 v[2:5], v[158:161], v[212:215], v[2:5]
	v_mfma_f32_16x16x32_bf16 v[46:49], v[146:149], v[170:173], v[70:73]
	v_mfma_f32_16x16x32_bf16 v[46:49], v[150:153], v[188:191], v[46:49]
	s_setprio 2
	s_barrier
	v_mfma_f32_16x16x32_bf16 v[54:57], v[154:157], v[170:173], v[66:69]
	v_mfma_f32_16x16x32_bf16 v[54:57], v[158:161], v[188:191], v[54:57]
	s_setprio 0
	ds_read_b128 v[58:61], v185
	ds_read_b128 v[62:65], v185 offset:1024
	ds_read_b128 v[66:69], v185 offset:2048
	ds_read_b128 v[70:73], v185 offset:3072
	ds_read_b128 v[146:149], v186
	ds_read_b128 v[150:153], v186 offset:1024
	ds_read_b128 v[154:157], v186 offset:2048
	ds_read_b128 v[158:161], v186 offset:3072
	ds_read_b128 v[170:173], v184 offset:32768
	ds_read_b128 v[188:191], v184 offset:33792
	ds_read_b128 v[192:195], v184 offset:34816
	ds_read_b128 v[196:199], v184 offset:35840
	ds_read_b128 v[200:203], v184 offset:36864
	ds_read_b128 v[204:207], v184 offset:37888
	ds_read_b128 v[208:211], v184 offset:38912
	ds_read_b128 v[212:215], v184 offset:39936
	s_mov_b32 s86, m0
	s_mov_b32 m0, s48
	s_nop 0
	global_load_lds_dwordx4 v176, s[36:37]
	s_mov_b32 m0, s86
	s_nop 0
	s_mov_b32 s86, m0
	s_mov_b32 m0, s59
	s_nop 0
	global_load_lds_dwordx4 v178, s[36:37]
	s_mov_b32 m0, s86
	s_add_u32 s36, s36, 0x80000
	s_addc_u32 s37, s37, 0
	s_mov_b32 s86, m0
	s_mov_b32 m0, s62
	s_nop 0
	global_load_lds_dwordx4 v176, s[36:37]
	s_mov_b32 m0, s86
	s_nop 0
	s_mov_b32 s86, m0
	s_mov_b32 m0, s63
	s_nop 0
	global_load_lds_dwordx4 v178, s[36:37]
	s_mov_b32 m0, s86
	s_waitcnt vmcnt(8)
	s_waitcnt lgkmcnt(0)
	s_barrier
	s_setprio 1
	s_waitcnt lgkmcnt(7)
	v_mfma_f32_16x16x32_bf16 v[142:145], v[58:61], v[170:173], v[142:145]
	v_mfma_f32_16x16x32_bf16 v[142:145], v[62:65], v[188:191], v[142:145]
	s_waitcnt lgkmcnt(5)
	v_mfma_f32_16x16x32_bf16 v[138:141], v[66:69], v[170:173], v[138:141]
	v_mfma_f32_16x16x32_bf16 v[138:141], v[70:73], v[188:191], v[138:141]
	s_waitcnt lgkmcnt(3)
	v_mfma_f32_16x16x32_bf16 v[126:129], v[58:61], v[192:195], v[126:129]
	v_mfma_f32_16x16x32_bf16 v[126:129], v[62:65], v[196:199], v[126:129]
	s_waitcnt lgkmcnt(1)
	v_mfma_f32_16x16x32_bf16 v[122:125], v[66:69], v[192:195], v[122:125]
	v_mfma_f32_16x16x32_bf16 v[122:125], v[70:73], v[196:199], v[122:125]
	v_mfma_f32_16x16x32_bf16 v[110:113], v[58:61], v[200:203], v[110:113]
	v_mfma_f32_16x16x32_bf16 v[110:113], v[62:65], v[204:207], v[110:113]
	v_mfma_f32_16x16x32_bf16 v[106:109], v[66:69], v[200:203], v[106:109]
	v_mfma_f32_16x16x32_bf16 v[106:109], v[70:73], v[204:207], v[106:109]
	v_mfma_f32_16x16x32_bf16 v[94:97], v[58:61], v[208:211], v[94:97]
	v_mfma_f32_16x16x32_bf16 v[94:97], v[62:65], v[212:215], v[94:97]
	s_waitcnt lgkmcnt(0)
	v_mfma_f32_16x16x32_bf16 v[90:93], v[66:69], v[208:211], v[90:93]
	v_mfma_f32_16x16x32_bf16 v[90:93], v[70:73], v[212:215], v[90:93]
	s_setprio 0
	s_setprio 1
	v_mfma_f32_16x16x32_bf16 v[134:137], v[146:149], v[170:173], v[134:137]
	v_mfma_f32_16x16x32_bf16 v[134:137], v[150:153], v[188:191], v[134:137]
	v_mfma_f32_16x16x32_bf16 v[130:133], v[154:157], v[170:173], v[130:133]
	v_mfma_f32_16x16x32_bf16 v[130:133], v[158:161], v[188:191], v[130:133]
	v_mfma_f32_16x16x32_bf16 v[118:121], v[146:149], v[192:195], v[118:121]
	v_mfma_f32_16x16x32_bf16 v[118:121], v[150:153], v[196:199], v[118:121]
	v_mfma_f32_16x16x32_bf16 v[114:117], v[154:157], v[192:195], v[114:117]
	v_mfma_f32_16x16x32_bf16 v[114:117], v[158:161], v[196:199], v[114:117]
	v_mfma_f32_16x16x32_bf16 v[102:105], v[146:149], v[200:203], v[102:105]
	v_mfma_f32_16x16x32_bf16 v[102:105], v[150:153], v[204:207], v[102:105]
	v_mfma_f32_16x16x32_bf16 v[98:101], v[154:157], v[200:203], v[98:101]
	v_mfma_f32_16x16x32_bf16 v[98:101], v[158:161], v[204:207], v[98:101]
	v_mfma_f32_16x16x32_bf16 v[86:89], v[146:149], v[208:211], v[86:89]
	v_mfma_f32_16x16x32_bf16 v[86:89], v[150:153], v[212:215], v[86:89]
	s_setprio 2
	s_barrier
	v_mfma_f32_16x16x32_bf16 v[82:85], v[154:157], v[208:211], v[82:85]
	v_mfma_f32_16x16x32_bf16 v[82:85], v[158:161], v[212:215], v[82:85]
	s_setprio 0
	ds_read_b128 v[170:173], v184 offset:49152
	ds_read_b128 v[188:191], v184 offset:50176
	ds_read_b128 v[192:195], v184 offset:51200
	ds_read_b128 v[196:199], v184 offset:52224
	ds_read_b128 v[200:203], v184 offset:53248
	ds_read_b128 v[204:207], v184 offset:54272
	ds_read_b128 v[208:211], v184 offset:55296
	ds_read_b128 v[212:215], v184 offset:56320
	s_add_u32 s36, s34, 0x80
	s_addc_u32 s37, s35, 0
	s_mov_b32 s86, m0
	s_mov_b32 m0, s64
	s_nop 0
	global_load_lds_dwordx4 v177, s[36:37]
	s_mov_b32 m0, s86
	s_add_u32 s34, s34, 0x80080
	s_mov_b32 s86, m0
	s_mov_b32 m0, s65
	s_nop 0
	global_load_lds_dwordx4 v179, s[36:37]
	s_mov_b32 m0, s86
	s_addc_u32 s35, s35, 0
	s_mov_b32 s36, m0
	s_mov_b32 m0, s66
	s_nop 0
	global_load_lds_dwordx4 v177, s[34:35]
	s_mov_b32 m0, s36
	s_nop 0
	s_mov_b32 s36, m0
	s_mov_b32 m0, s67
	s_nop 0
	global_load_lds_dwordx4 v179, s[34:35]
	s_mov_b32 m0, s36
	s_waitcnt vmcnt(4)
	s_waitcnt lgkmcnt(0)
	s_barrier
	s_setprio 1
	s_waitcnt lgkmcnt(7)
	v_mfma_f32_16x16x32_bf16 v[78:81], v[58:61], v[170:173], v[78:81]
	v_mfma_f32_16x16x32_bf16 v[78:81], v[62:65], v[188:191], v[78:81]
	s_waitcnt lgkmcnt(5)
	v_mfma_f32_16x16x32_bf16 v[74:77], v[66:69], v[170:173], v[74:77]
	v_mfma_f32_16x16x32_bf16 v[74:77], v[70:73], v[188:191], v[74:77]
	s_waitcnt lgkmcnt(3)
	v_mfma_f32_16x16x32_bf16 v[50:53], v[58:61], v[192:195], v[50:53]
	v_mfma_f32_16x16x32_bf16 v[50:53], v[62:65], v[196:199], v[50:53]
	s_waitcnt lgkmcnt(1)
	v_mfma_f32_16x16x32_bf16 v[42:45], v[66:69], v[192:195], v[42:45]
	v_mfma_f32_16x16x32_bf16 v[42:45], v[70:73], v[196:199], v[42:45]
	v_mfma_f32_16x16x32_bf16 v[30:33], v[58:61], v[200:203], v[30:33]
	v_mfma_f32_16x16x32_bf16 v[30:33], v[62:65], v[204:207], v[30:33]
	v_mfma_f32_16x16x32_bf16 v[26:29], v[66:69], v[200:203], v[26:29]
	v_mfma_f32_16x16x32_bf16 v[26:29], v[70:73], v[204:207], v[26:29]
	v_mfma_f32_16x16x32_bf16 v[14:17], v[58:61], v[208:211], v[14:17]
	v_mfma_f32_16x16x32_bf16 v[14:17], v[62:65], v[212:215], v[14:17]
	s_waitcnt lgkmcnt(0)
	v_mfma_f32_16x16x32_bf16 v[10:13], v[66:69], v[208:211], v[10:13]
	v_mfma_f32_16x16x32_bf16 v[10:13], v[70:73], v[212:215], v[10:13]
	s_setprio 0
	s_setprio 1
	v_mfma_f32_16x16x32_bf16 v[46:49], v[146:149], v[170:173], v[46:49]
	v_mfma_f32_16x16x32_bf16 v[70:73], v[150:153], v[188:191], v[46:49]
	v_mfma_f32_16x16x32_bf16 v[46:49], v[154:157], v[170:173], v[54:57]
	v_mfma_f32_16x16x32_bf16 v[66:69], v[158:161], v[188:191], v[46:49]
	v_mfma_f32_16x16x32_bf16 v[38:41], v[146:149], v[192:195], v[38:41]
	v_mfma_f32_16x16x32_bf16 v[38:41], v[150:153], v[196:199], v[38:41]
	v_mfma_f32_16x16x32_bf16 v[34:37], v[154:157], v[192:195], v[34:37]
	v_mfma_f32_16x16x32_bf16 v[34:37], v[158:161], v[196:199], v[34:37]
	v_mfma_f32_16x16x32_bf16 v[22:25], v[146:149], v[200:203], v[22:25]
	v_mfma_f32_16x16x32_bf16 v[22:25], v[150:153], v[204:207], v[22:25]
	v_mfma_f32_16x16x32_bf16 v[18:21], v[154:157], v[200:203], v[18:21]
	v_mfma_f32_16x16x32_bf16 v[18:21], v[158:161], v[204:207], v[18:21]
	v_mfma_f32_16x16x32_bf16 v[6:9], v[146:149], v[208:211], v[6:9]
	v_mfma_f32_16x16x32_bf16 v[6:9], v[150:153], v[212:215], v[6:9]
	s_setprio 2
	s_barrier
	v_mfma_f32_16x16x32_bf16 v[2:5], v[154:157], v[208:211], v[2:5]
	v_mfma_f32_16x16x32_bf16 v[2:5], v[158:161], v[212:215], v[2:5]
	s_setprio 0
	s_add_i32 s83, s83, 2
	s_add_u32 s79, s79, 0x100
	s_addc_u32 s80, s80, 0
	s_add_u32 s30, s30, 0x100
	s_addc_u32 s31, s31, 0
	s_add_u32 s81, s81, 0x100
	s_addc_u32 s82, s82, 0
	s_cmp_gt_u32 s83, 29
	s_cbranch_scc0 .LBB0_1538
	s_and_b64 vcc, exec, s[16:17]
	s_cbranch_vccz .LBB0_1541
	s_barrier

.LBB0_2145:
	s_ashr_i32 s25, s24, 31
	s_lshl_b64 s[26:27], s[24:25], 20
	s_add_u32 s26, s33, s26
	s_addc_u32 s27, s42, s27
	s_and_b64 s[28:29], s[2:3], exec
	s_cselect_b32 s5, s27, s37
	s_cselect_b32 s25, s26, s36
	s_ashr_i32 s23, s22, 31
	s_lshl_b64 s[28:29], s[22:23], 20
	s_add_u32 s28, s43, s28
	s_addc_u32 s29, s46, s29
	s_and_b64 s[40:41], s[2:3], exec
	s_cselect_b32 s23, s29, s35
	s_cselect_b32 s31, s28, s34
	s_add_u32 s77, s34, 0x100
	s_addc_u32 s78, s35, 0
	s_add_u32 s34, s36, 0x80080
	s_addc_u32 s35, s37, 0
	s_add_u32 s79, s36, 0x100
	s_addc_u32 s80, s37, 0
	s_mov_b32 s81, -2
	s_waitcnt vmcnt(25)
	s_waitcnt vmcnt(24)
	s_waitcnt vmcnt(4)
	s_waitcnt vmcnt(2)
	s_waitcnt vmcnt(1)
	s_waitcnt vmcnt(0)
	ds_read_b128 v[42:45], v181
	ds_read_b128 v[46:49], v181 offset:1024
	ds_read_b128 v[58:61], v181 offset:2048
	ds_read_b128 v[62:65], v181 offset:3072
	ds_read_b128 v[146:149], v182
	ds_read_b128 v[150:153], v182 offset:1024
	ds_read_b128 v[154:157], v182 offset:2048
	ds_read_b128 v[158:161], v182 offset:3072
	s_cmp_eq_u32 s81, 28
	s_cselect_b32 s37, s23, s78
	s_cselect_b32 s36, s31, s77
	s_cselect_b32 s41, s5, s80
	s_cselect_b32 s40, s25, s79
	ds_read_b128 v[170:173], v183
	ds_read_b128 v[188:191], v183 offset:1024
	ds_read_b128 v[192:195], v183 offset:2048
	ds_read_b128 v[196:199], v183 offset:3072
	ds_read_b128 v[200:203], v183 offset:4096
	ds_read_b128 v[204:207], v183 offset:5120
	ds_read_b128 v[208:211], v183 offset:6144
	ds_read_b128 v[212:215], v183 offset:7168
	s_add_u32 s82, s34, 0xfff80000
	s_addc_u32 s83, s35, -1
	s_mov_b32 s86, m0
	s_mov_b32 m0, s70
	s_nop 0
	global_load_lds_dwordx4 v1, s[82:83]
	s_mov_b32 m0, s86
	s_nop 0
	s_mov_b32 s86, m0
	s_mov_b32 m0, s73
	s_nop 0
	global_load_lds_dwordx4 v177, s[82:83]
	s_mov_b32 m0, s86
	s_mov_b32 s82, m0
	s_mov_b32 m0, s71
	s_nop 0
	global_load_lds_dwordx4 v1, s[34:35]
	s_mov_b32 m0, s82
	s_nop 0
	s_mov_b32 s82, m0
	s_mov_b32 m0, s74
	s_nop 0
	global_load_lds_dwordx4 v177, s[34:35]
	s_mov_b32 m0, s82
	s_waitcnt vmcnt(8)
	s_waitcnt lgkmcnt(0)
	s_barrier
	s_setprio 1
	s_waitcnt lgkmcnt(7)
	v_mfma_f32_16x16x32_bf16 v[142:145], v[42:45], v[170:173], 0
	v_mfma_f32_16x16x32_bf16 v[142:145], v[46:49], v[188:191], v[142:145]
	s_waitcnt lgkmcnt(5)
	v_mfma_f32_16x16x32_bf16 v[138:141], v[58:61], v[170:173], 0
	v_mfma_f32_16x16x32_bf16 v[138:141], v[62:65], v[188:191], v[138:141]
	s_waitcnt lgkmcnt(3)
	v_mfma_f32_16x16x32_bf16 v[126:129], v[42:45], v[192:195], 0
	v_mfma_f32_16x16x32_bf16 v[126:129], v[46:49], v[196:199], v[126:129]
	s_waitcnt lgkmcnt(1)
	v_mfma_f32_16x16x32_bf16 v[122:125], v[58:61], v[192:195], 0
	v_mfma_f32_16x16x32_bf16 v[122:125], v[62:65], v[196:199], v[122:125]
	v_mfma_f32_16x16x32_bf16 v[110:113], v[42:45], v[200:203], 0
	v_mfma_f32_16x16x32_bf16 v[110:113], v[46:49], v[204:207], v[110:113]
	v_mfma_f32_16x16x32_bf16 v[106:109], v[58:61], v[200:203], 0
	v_mfma_f32_16x16x32_bf16 v[106:109], v[62:65], v[204:207], v[106:109]
	v_mfma_f32_16x16x32_bf16 v[94:97], v[42:45], v[208:211], 0
	v_mfma_f32_16x16x32_bf16 v[94:97], v[46:49], v[212:215], v[94:97]
	s_waitcnt lgkmcnt(0)
	v_mfma_f32_16x16x32_bf16 v[90:93], v[58:61], v[208:211], 0
	v_mfma_f32_16x16x32_bf16 v[90:93], v[62:65], v[212:215], v[90:93]
	s_setprio 0
	s_setprio 1
	v_mfma_f32_16x16x32_bf16 v[134:137], v[146:149], v[170:173], 0
	v_mfma_f32_16x16x32_bf16 v[134:137], v[150:153], v[188:191], v[134:137]
	v_mfma_f32_16x16x32_bf16 v[130:133], v[154:157], v[170:173], 0
	v_mfma_f32_16x16x32_bf16 v[130:133], v[158:161], v[188:191], v[130:133]
	v_mfma_f32_16x16x32_bf16 v[118:121], v[146:149], v[192:195], 0
	v_mfma_f32_16x16x32_bf16 v[118:121], v[150:153], v[196:199], v[118:121]
	v_mfma_f32_16x16x32_bf16 v[114:117], v[154:157], v[192:195], 0
	v_mfma_f32_16x16x32_bf16 v[114:117], v[158:161], v[196:199], v[114:117]
	v_mfma_f32_16x16x32_bf16 v[102:105], v[146:149], v[200:203], 0
	v_mfma_f32_16x16x32_bf16 v[102:105], v[150:153], v[204:207], v[102:105]
	v_mfma_f32_16x16x32_bf16 v[98:101], v[154:157], v[200:203], 0
	v_mfma_f32_16x16x32_bf16 v[98:101], v[158:161], v[204:207], v[98:101]
	v_mfma_f32_16x16x32_bf16 v[86:89], v[146:149], v[208:211], 0
	v_mfma_f32_16x16x32_bf16 v[86:89], v[150:153], v[212:215], v[86:89]
	s_setprio 2
	s_barrier
	v_mfma_f32_16x16x32_bf16 v[82:85], v[154:157], v[208:211], 0
	v_mfma_f32_16x16x32_bf16 v[82:85], v[158:161], v[212:215], v[82:85]
	s_setprio 0
	ds_read_b128 v[170:173], v183 offset:16384
	ds_read_b128 v[188:191], v183 offset:17408
	ds_read_b128 v[192:195], v183 offset:18432
	ds_read_b128 v[196:199], v183 offset:19456
	ds_read_b128 v[200:203], v183 offset:20480
	ds_read_b128 v[204:207], v183 offset:21504
	ds_read_b128 v[208:211], v183 offset:22528
	ds_read_b128 v[212:215], v183 offset:23552
	s_mov_b32 s82, m0
	s_mov_b32 m0, s49
	s_nop 0
	global_load_lds_dwordx4 v176, s[36:37]
	s_mov_b32 m0, s82
	s_nop 0
	s_mov_b32 s82, m0
	s_mov_b32 m0, s56
	s_nop 0
	global_load_lds_dwordx4 v178, s[36:37]
	s_mov_b32 m0, s82
	s_add_u32 s82, s36, 0x80000
	s_addc_u32 s83, s37, 0
	s_mov_b32 s86, m0
	s_mov_b32 m0, s57
	s_nop 0
	global_load_lds_dwordx4 v176, s[82:83]
	s_mov_b32 m0, s86
	s_nop 0
	s_mov_b32 s86, m0
	s_mov_b32 m0, s58
	s_nop 0
	global_load_lds_dwordx4 v178, s[82:83]
	s_mov_b32 m0, s86
	s_waitcnt vmcnt(4)
	s_waitcnt lgkmcnt(0)
	s_barrier
	s_setprio 1
	s_waitcnt lgkmcnt(7)
	v_mfma_f32_16x16x32_bf16 v[78:81], v[42:45], v[170:173], 0
	v_mfma_f32_16x16x32_bf16 v[78:81], v[46:49], v[188:191], v[78:81]
	s_waitcnt lgkmcnt(5)
	v_mfma_f32_16x16x32_bf16 v[74:77], v[58:61], v[170:173], 0
	v_mfma_f32_16x16x32_bf16 v[74:77], v[62:65], v[188:191], v[74:77]
	s_waitcnt lgkmcnt(3)
	v_mfma_f32_16x16x32_bf16 v[54:57], v[42:45], v[192:195], 0
	v_mfma_f32_16x16x32_bf16 v[54:57], v[46:49], v[196:199], v[54:57]
	s_waitcnt lgkmcnt(1)
	v_mfma_f32_16x16x32_bf16 v[50:53], v[58:61], v[192:195], 0
	v_mfma_f32_16x16x32_bf16 v[50:53], v[62:65], v[196:199], v[50:53]
	v_mfma_f32_16x16x32_bf16 v[30:33], v[42:45], v[200:203], 0
	v_mfma_f32_16x16x32_bf16 v[30:33], v[46:49], v[204:207], v[30:33]
	v_mfma_f32_16x16x32_bf16 v[26:29], v[58:61], v[200:203], 0
	v_mfma_f32_16x16x32_bf16 v[26:29], v[62:65], v[204:207], v[26:29]
	v_mfma_f32_16x16x32_bf16 v[14:17], v[42:45], v[208:211], 0
	v_mfma_f32_16x16x32_bf16 v[14:17], v[46:49], v[212:215], v[14:17]
	s_waitcnt lgkmcnt(0)
	v_mfma_f32_16x16x32_bf16 v[10:13], v[58:61], v[208:211], 0
	v_mfma_f32_16x16x32_bf16 v[10:13], v[62:65], v[212:215], v[10:13]
	s_setprio 0
	s_setprio 1
	v_mfma_f32_16x16x32_bf16 v[38:41], v[146:149], v[192:195], 0
	v_mfma_f32_16x16x32_bf16 v[38:41], v[150:153], v[196:199], v[38:41]
	v_mfma_f32_16x16x32_bf16 v[34:37], v[154:157], v[192:195], 0
	v_mfma_f32_16x16x32_bf16 v[34:37], v[158:161], v[196:199], v[34:37]
	v_mfma_f32_16x16x32_bf16 v[22:25], v[146:149], v[200:203], 0
	v_mfma_f32_16x16x32_bf16 v[22:25], v[150:153], v[204:207], v[22:25]
	v_mfma_f32_16x16x32_bf16 v[18:21], v[154:157], v[200:203], 0
	v_mfma_f32_16x16x32_bf16 v[18:21], v[158:161], v[204:207], v[18:21]
	v_mfma_f32_16x16x32_bf16 v[6:9], v[146:149], v[208:211], 0
	v_mfma_f32_16x16x32_bf16 v[6:9], v[150:153], v[212:215], v[6:9]
	v_mfma_f32_16x16x32_bf16 v[2:5], v[154:157], v[208:211], 0
	v_mfma_f32_16x16x32_bf16 v[2:5], v[158:161], v[212:215], v[2:5]
	v_mfma_f32_16x16x32_bf16 v[42:45], v[146:149], v[170:173], 0
	v_mfma_f32_16x16x32_bf16 v[42:45], v[150:153], v[188:191], v[42:45]
	s_setprio 2
	s_barrier
	v_mfma_f32_16x16x32_bf16 v[46:49], v[154:157], v[170:173], 0
	v_mfma_f32_16x16x32_bf16 v[46:49], v[158:161], v[188:191], v[46:49]
	s_setprio 0
	ds_read_b128 v[58:61], v184
	ds_read_b128 v[62:65], v184 offset:1024
	ds_read_b128 v[66:69], v184 offset:2048
	ds_read_b128 v[70:73], v184 offset:3072
	ds_read_b128 v[146:149], v185
	ds_read_b128 v[150:153], v185 offset:1024
	ds_read_b128 v[154:157], v185 offset:2048
	ds_read_b128 v[158:161], v185 offset:3072
	ds_read_b128 v[170:173], v183 offset:32768
	ds_read_b128 v[188:191], v183 offset:33792
	ds_read_b128 v[192:195], v183 offset:34816
	ds_read_b128 v[196:199], v183 offset:35840
	ds_read_b128 v[200:203], v183 offset:36864
	ds_read_b128 v[204:207], v183 offset:37888
	ds_read_b128 v[208:211], v183 offset:38912
	ds_read_b128 v[212:215], v183 offset:39936
	s_mov_b32 s82, m0
	s_mov_b32 m0, s48
	s_nop 0
	global_load_lds_dwordx4 v1, s[40:41]
	s_mov_b32 m0, s82
	s_nop 0
	s_mov_b32 s82, m0
	s_mov_b32 m0, s59
	s_nop 0
	global_load_lds_dwordx4 v177, s[40:41]
	s_mov_b32 m0, s82
	s_add_u32 s40, s40, 0x80000
	s_addc_u32 s41, s41, 0
	s_mov_b32 s82, m0
	s_mov_b32 m0, s62
	s_nop 0
	global_load_lds_dwordx4 v1, s[40:41]
	s_mov_b32 m0, s82
	s_nop 0
	s_mov_b32 s82, m0
	s_mov_b32 m0, s63
	s_nop 0
	global_load_lds_dwordx4 v177, s[40:41]
	s_mov_b32 m0, s82
	s_waitcnt vmcnt(8)
	s_waitcnt lgkmcnt(0)
	s_barrier
	s_setprio 1
	s_waitcnt lgkmcnt(7)
	v_mfma_f32_16x16x32_bf16 v[142:145], v[58:61], v[170:173], v[142:145]
	v_mfma_f32_16x16x32_bf16 v[142:145], v[62:65], v[188:191], v[142:145]
	s_waitcnt lgkmcnt(5)
	v_mfma_f32_16x16x32_bf16 v[138:141], v[66:69], v[170:173], v[138:141]
	v_mfma_f32_16x16x32_bf16 v[138:141], v[70:73], v[188:191], v[138:141]
	s_waitcnt lgkmcnt(3)
	v_mfma_f32_16x16x32_bf16 v[126:129], v[58:61], v[192:195], v[126:129]
	v_mfma_f32_16x16x32_bf16 v[126:129], v[62:65], v[196:199], v[126:129]
	s_waitcnt lgkmcnt(1)
	v_mfma_f32_16x16x32_bf16 v[122:125], v[66:69], v[192:195], v[122:125]
	v_mfma_f32_16x16x32_bf16 v[122:125], v[70:73], v[196:199], v[122:125]
	v_mfma_f32_16x16x32_bf16 v[110:113], v[58:61], v[200:203], v[110:113]
	v_mfma_f32_16x16x32_bf16 v[110:113], v[62:65], v[204:207], v[110:113]
	v_mfma_f32_16x16x32_bf16 v[106:109], v[66:69], v[200:203], v[106:109]
	v_mfma_f32_16x16x32_bf16 v[106:109], v[70:73], v[204:207], v[106:109]
	v_mfma_f32_16x16x32_bf16 v[94:97], v[58:61], v[208:211], v[94:97]
	v_mfma_f32_16x16x32_bf16 v[94:97], v[62:65], v[212:215], v[94:97]
	s_waitcnt lgkmcnt(0)
	v_mfma_f32_16x16x32_bf16 v[90:93], v[66:69], v[208:211], v[90:93]
	v_mfma_f32_16x16x32_bf16 v[90:93], v[70:73], v[212:215], v[90:93]
	s_setprio 0
	s_setprio 1
	v_mfma_f32_16x16x32_bf16 v[134:137], v[146:149], v[170:173], v[134:137]
	v_mfma_f32_16x16x32_bf16 v[134:137], v[150:153], v[188:191], v[134:137]
	v_mfma_f32_16x16x32_bf16 v[130:133], v[154:157], v[170:173], v[130:133]
	v_mfma_f32_16x16x32_bf16 v[130:133], v[158:161], v[188:191], v[130:133]
	v_mfma_f32_16x16x32_bf16 v[118:121], v[146:149], v[192:195], v[118:121]
	v_mfma_f32_16x16x32_bf16 v[118:121], v[150:153], v[196:199], v[118:121]
	v_mfma_f32_16x16x32_bf16 v[114:117], v[154:157], v[192:195], v[114:117]
	v_mfma_f32_16x16x32_bf16 v[114:117], v[158:161], v[196:199], v[114:117]
	v_mfma_f32_16x16x32_bf16 v[102:105], v[146:149], v[200:203], v[102:105]
	v_mfma_f32_16x16x32_bf16 v[102:105], v[150:153], v[204:207], v[102:105]
	v_mfma_f32_16x16x32_bf16 v[98:101], v[154:157], v[200:203], v[98:101]
	v_mfma_f32_16x16x32_bf16 v[98:101], v[158:161], v[204:207], v[98:101]
	v_mfma_f32_16x16x32_bf16 v[86:89], v[146:149], v[208:211], v[86:89]
	v_mfma_f32_16x16x32_bf16 v[86:89], v[150:153], v[212:215], v[86:89]
	s_setprio 2
	s_barrier
	v_mfma_f32_16x16x32_bf16 v[82:85], v[154:157], v[208:211], v[82:85]
	v_mfma_f32_16x16x32_bf16 v[82:85], v[158:161], v[212:215], v[82:85]
	s_setprio 0
	ds_read_b128 v[170:173], v183 offset:49152
	ds_read_b128 v[188:191], v183 offset:50176
	ds_read_b128 v[192:195], v183 offset:51200
	ds_read_b128 v[196:199], v183 offset:52224
	ds_read_b128 v[200:203], v183 offset:53248
	ds_read_b128 v[204:207], v183 offset:54272
	ds_read_b128 v[208:211], v183 offset:55296
	ds_read_b128 v[212:215], v183 offset:56320
	s_add_u32 s40, s36, 0x80
	s_addc_u32 s41, s37, 0
	s_mov_b32 s82, m0
	s_mov_b32 m0, s64
	s_nop 0
	global_load_lds_dwordx4 v176, s[40:41]
	s_mov_b32 m0, s82
	s_add_u32 s36, s36, 0x80080
	s_mov_b32 s82, m0
	s_mov_b32 m0, s65
	s_nop 0
	global_load_lds_dwordx4 v178, s[40:41]
	s_mov_b32 m0, s82
	s_addc_u32 s37, s37, 0
	s_mov_b32 s40, m0
	s_mov_b32 m0, s66
	s_nop 0
	global_load_lds_dwordx4 v176, s[36:37]
	s_mov_b32 m0, s40
	s_nop 0
	s_mov_b32 s40, m0
	s_mov_b32 m0, s67
	s_nop 0
	global_load_lds_dwordx4 v178, s[36:37]
	s_mov_b32 m0, s40
	s_waitcnt vmcnt(4)
	s_waitcnt lgkmcnt(0)
	s_barrier
	s_setprio 1
	s_waitcnt lgkmcnt(7)
	v_mfma_f32_16x16x32_bf16 v[78:81], v[58:61], v[170:173], v[78:81]
	v_mfma_f32_16x16x32_bf16 v[78:81], v[62:65], v[188:191], v[78:81]
	s_waitcnt lgkmcnt(5)
	v_mfma_f32_16x16x32_bf16 v[74:77], v[66:69], v[170:173], v[74:77]
	v_mfma_f32_16x16x32_bf16 v[74:77], v[70:73], v[188:191], v[74:77]
	s_waitcnt lgkmcnt(3)
	v_mfma_f32_16x16x32_bf16 v[54:57], v[58:61], v[192:195], v[54:57]
	v_mfma_f32_16x16x32_bf16 v[54:57], v[62:65], v[196:199], v[54:57]
	s_waitcnt lgkmcnt(1)
	v_mfma_f32_16x16x32_bf16 v[50:53], v[66:69], v[192:195], v[50:53]
	v_mfma_f32_16x16x32_bf16 v[50:53], v[70:73], v[196:199], v[50:53]
	v_mfma_f32_16x16x32_bf16 v[30:33], v[58:61], v[200:203], v[30:33]
	v_mfma_f32_16x16x32_bf16 v[30:33], v[62:65], v[204:207], v[30:33]
	v_mfma_f32_16x16x32_bf16 v[26:29], v[66:69], v[200:203], v[26:29]
	v_mfma_f32_16x16x32_bf16 v[26:29], v[70:73], v[204:207], v[26:29]
	v_mfma_f32_16x16x32_bf16 v[14:17], v[58:61], v[208:211], v[14:17]
	v_mfma_f32_16x16x32_bf16 v[14:17], v[62:65], v[212:215], v[14:17]
	s_waitcnt lgkmcnt(0)
	v_mfma_f32_16x16x32_bf16 v[10:13], v[66:69], v[208:211], v[10:13]
	v_mfma_f32_16x16x32_bf16 v[10:13], v[70:73], v[212:215], v[10:13]
	s_setprio 0
	s_setprio 1
	v_mfma_f32_16x16x32_bf16 v[42:45], v[146:149], v[170:173], v[42:45]
	v_mfma_f32_16x16x32_bf16 v[70:73], v[150:153], v[188:191], v[42:45]
	v_mfma_f32_16x16x32_bf16 v[42:45], v[154:157], v[170:173], v[46:49]
	v_mfma_f32_16x16x32_bf16 v[66:69], v[158:161], v[188:191], v[42:45]
	v_mfma_f32_16x16x32_bf16 v[38:41], v[146:149], v[192:195], v[38:41]
	v_mfma_f32_16x16x32_bf16 v[38:41], v[150:153], v[196:199], v[38:41]
	v_mfma_f32_16x16x32_bf16 v[34:37], v[154:157], v[192:195], v[34:37]
	v_mfma_f32_16x16x32_bf16 v[34:37], v[158:161], v[196:199], v[34:37]
	v_mfma_f32_16x16x32_bf16 v[22:25], v[146:149], v[200:203], v[22:25]
	v_mfma_f32_16x16x32_bf16 v[22:25], v[150:153], v[204:207], v[22:25]
	v_mfma_f32_16x16x32_bf16 v[18:21], v[154:157], v[200:203], v[18:21]
	v_mfma_f32_16x16x32_bf16 v[18:21], v[158:161], v[204:207], v[18:21]
	v_mfma_f32_16x16x32_bf16 v[6:9], v[146:149], v[208:211], v[6:9]
	v_mfma_f32_16x16x32_bf16 v[6:9], v[150:153], v[212:215], v[6:9]
	s_setprio 2
	s_barrier
	v_mfma_f32_16x16x32_bf16 v[2:5], v[154:157], v[208:211], v[2:5]
	v_mfma_f32_16x16x32_bf16 v[2:5], v[158:161], v[212:215], v[2:5]
	s_setprio 0
	s_add_i32 s81, s81, 2
	s_add_u32 s77, s77, 0x100
	s_addc_u32 s78, s78, 0
	s_add_u32 s34, s34, 0x100
	s_addc_u32 s35, s35, 0
	s_add_u32 s79, s79, 0x100
	s_addc_u32 s80, s80, 0
	s_cmp_gt_u32 s81, 29
	.p2align 6
.LBB0_2146:
	ds_read_b128 v[42:45], v181
	ds_read_b128 v[46:49], v181 offset:1024
	ds_read_b128 v[58:61], v181 offset:2048
	ds_read_b128 v[62:65], v181 offset:3072
	ds_read_b128 v[146:149], v182
	ds_read_b128 v[150:153], v182 offset:1024
	ds_read_b128 v[154:157], v182 offset:2048
	ds_read_b128 v[158:161], v182 offset:3072
	s_cmp_eq_u32 s81, 28
	s_cselect_b32 s37, s23, s78
	s_cselect_b32 s36, s31, s77
	s_cselect_b32 s41, s5, s80
	s_cselect_b32 s40, s25, s79
	ds_read_b128 v[170:173], v183
	ds_read_b128 v[188:191], v183 offset:1024
	ds_read_b128 v[192:195], v183 offset:2048
	ds_read_b128 v[196:199], v183 offset:3072
	ds_read_b128 v[200:203], v183 offset:4096
	ds_read_b128 v[204:207], v183 offset:5120
	ds_read_b128 v[208:211], v183 offset:6144
	ds_read_b128 v[212:215], v183 offset:7168
	s_add_u32 s82, s34, 0xfff80000
	s_addc_u32 s83, s35, -1
	s_mov_b32 s86, m0
	s_mov_b32 m0, s70
	s_nop 0
	global_load_lds_dwordx4 v1, s[82:83]
	s_mov_b32 m0, s86
	s_nop 0
	s_mov_b32 s86, m0
	s_mov_b32 m0, s73
	s_nop 0
	global_load_lds_dwordx4 v177, s[82:83]
	s_mov_b32 m0, s86
	s_mov_b32 s82, m0
	s_mov_b32 m0, s71
	s_nop 0
	global_load_lds_dwordx4 v1, s[34:35]
	s_mov_b32 m0, s82
	s_nop 0
	s_mov_b32 s82, m0
	s_mov_b32 m0, s74
	s_nop 0
	global_load_lds_dwordx4 v177, s[34:35]
	s_mov_b32 m0, s82
	s_waitcnt vmcnt(8)
	s_waitcnt lgkmcnt(0)
	s_barrier
	s_setprio 1
	s_waitcnt lgkmcnt(7)
	v_mfma_f32_16x16x32_bf16 v[142:145], v[42:45], v[170:173], v[142:145]
	v_mfma_f32_16x16x32_bf16 v[142:145], v[46:49], v[188:191], v[142:145]
	s_waitcnt lgkmcnt(5)
	v_mfma_f32_16x16x32_bf16 v[138:141], v[58:61], v[170:173], v[138:141]
	v_mfma_f32_16x16x32_bf16 v[138:141], v[62:65], v[188:191], v[138:141]
	s_waitcnt lgkmcnt(3)
	v_mfma_f32_16x16x32_bf16 v[126:129], v[42:45], v[192:195], v[126:129]
	v_mfma_f32_16x16x32_bf16 v[126:129], v[46:49], v[196:199], v[126:129]
	s_waitcnt lgkmcnt(1)
	v_mfma_f32_16x16x32_bf16 v[122:125], v[58:61], v[192:195], v[122:125]
	v_mfma_f32_16x16x32_bf16 v[122:125], v[62:65], v[196:199], v[122:125]
	v_mfma_f32_16x16x32_bf16 v[110:113], v[42:45], v[200:203], v[110:113]
	v_mfma_f32_16x16x32_bf16 v[110:113], v[46:49], v[204:207], v[110:113]
	v_mfma_f32_16x16x32_bf16 v[106:109], v[58:61], v[200:203], v[106:109]
	v_mfma_f32_16x16x32_bf16 v[106:109], v[62:65], v[204:207], v[106:109]
	v_mfma_f32_16x16x32_bf16 v[94:97], v[42:45], v[208:211], v[94:97]
	v_mfma_f32_16x16x32_bf16 v[94:97], v[46:49], v[212:215], v[94:97]
	s_waitcnt lgkmcnt(0)
	v_mfma_f32_16x16x32_bf16 v[90:93], v[58:61], v[208:211], v[90:93]
	v_mfma_f32_16x16x32_bf16 v[90:93], v[62:65], v[212:215], v[90:93]
	s_setprio 0
	s_setprio 1
	v_mfma_f32_16x16x32_bf16 v[134:137], v[146:149], v[170:173], v[134:137]
	v_mfma_f32_16x16x32_bf16 v[134:137], v[150:153], v[188:191], v[134:137]
	v_mfma_f32_16x16x32_bf16 v[130:133], v[154:157], v[170:173], v[130:133]
	v_mfma_f32_16x16x32_bf16 v[130:133], v[158:161], v[188:191], v[130:133]
	v_mfma_f32_16x16x32_bf16 v[118:121], v[146:149], v[192:195], v[118:121]
	v_mfma_f32_16x16x32_bf16 v[118:121], v[150:153], v[196:199], v[118:121]
	v_mfma_f32_16x16x32_bf16 v[114:117], v[154:157], v[192:195], v[114:117]
	v_mfma_f32_16x16x32_bf16 v[114:117], v[158:161], v[196:199], v[114:117]
	v_mfma_f32_16x16x32_bf16 v[102:105], v[146:149], v[200:203], v[102:105]
	v_mfma_f32_16x16x32_bf16 v[102:105], v[150:153], v[204:207], v[102:105]
	v_mfma_f32_16x16x32_bf16 v[98:101], v[154:157], v[200:203], v[98:101]
	v_mfma_f32_16x16x32_bf16 v[98:101], v[158:161], v[204:207], v[98:101]
	v_mfma_f32_16x16x32_bf16 v[86:89], v[146:149], v[208:211], v[86:89]
	v_mfma_f32_16x16x32_bf16 v[86:89], v[150:153], v[212:215], v[86:89]
	s_setprio 2
	s_barrier
	v_mfma_f32_16x16x32_bf16 v[82:85], v[154:157], v[208:211], v[82:85]
	v_mfma_f32_16x16x32_bf16 v[82:85], v[158:161], v[212:215], v[82:85]
	s_setprio 0
	ds_read_b128 v[170:173], v183 offset:16384
	ds_read_b128 v[188:191], v183 offset:17408
	ds_read_b128 v[192:195], v183 offset:18432
	ds_read_b128 v[196:199], v183 offset:19456
	ds_read_b128 v[200:203], v183 offset:20480
	ds_read_b128 v[204:207], v183 offset:21504
	ds_read_b128 v[208:211], v183 offset:22528
	ds_read_b128 v[212:215], v183 offset:23552
	s_mov_b32 s82, m0
	s_mov_b32 m0, s49
	s_nop 0
	global_load_lds_dwordx4 v176, s[36:37]
	s_mov_b32 m0, s82
	s_nop 0
	s_mov_b32 s82, m0
	s_mov_b32 m0, s56
	s_nop 0
	global_load_lds_dwordx4 v178, s[36:37]
	s_mov_b32 m0, s82
	s_add_u32 s82, s36, 0x80000
	s_addc_u32 s83, s37, 0
	s_mov_b32 s86, m0
	s_mov_b32 m0, s57
	s_nop 0
	global_load_lds_dwordx4 v176, s[82:83]
	s_mov_b32 m0, s86
	s_nop 0
	s_mov_b32 s86, m0
	s_mov_b32 m0, s58
	s_nop 0
	global_load_lds_dwordx4 v178, s[82:83]
	s_mov_b32 m0, s86
	s_waitcnt vmcnt(4)
	s_waitcnt lgkmcnt(0)
	s_barrier
	s_setprio 1
	s_waitcnt lgkmcnt(7)
	v_mfma_f32_16x16x32_bf16 v[78:81], v[42:45], v[170:173], v[78:81]
	v_mfma_f32_16x16x32_bf16 v[78:81], v[46:49], v[188:191], v[78:81]
	s_waitcnt lgkmcnt(5)
	v_mfma_f32_16x16x32_bf16 v[74:77], v[58:61], v[170:173], v[74:77]
	v_mfma_f32_16x16x32_bf16 v[74:77], v[62:65], v[188:191], v[74:77]
	s_waitcnt lgkmcnt(3)
	v_mfma_f32_16x16x32_bf16 v[54:57], v[42:45], v[192:195], v[54:57]
	v_mfma_f32_16x16x32_bf16 v[54:57], v[46:49], v[196:199], v[54:57]
	s_waitcnt lgkmcnt(1)
	v_mfma_f32_16x16x32_bf16 v[50:53], v[58:61], v[192:195], v[50:53]
	v_mfma_f32_16x16x32_bf16 v[50:53], v[62:65], v[196:199], v[50:53]
	v_mfma_f32_16x16x32_bf16 v[30:33], v[42:45], v[200:203], v[30:33]
	v_mfma_f32_16x16x32_bf16 v[30:33], v[46:49], v[204:207], v[30:33]
	v_mfma_f32_16x16x32_bf16 v[26:29], v[58:61], v[200:203], v[26:29]
	v_mfma_f32_16x16x32_bf16 v[26:29], v[62:65], v[204:207], v[26:29]
	v_mfma_f32_16x16x32_bf16 v[14:17], v[42:45], v[208:211], v[14:17]
	v_mfma_f32_16x16x32_bf16 v[14:17], v[46:49], v[212:215], v[14:17]
	s_waitcnt lgkmcnt(0)
	v_mfma_f32_16x16x32_bf16 v[10:13], v[58:61], v[208:211], v[10:13]
	v_mfma_f32_16x16x32_bf16 v[10:13], v[62:65], v[212:215], v[10:13]
	s_setprio 0
	s_setprio 1
	v_mfma_f32_16x16x32_bf16 v[38:41], v[146:149], v[192:195], v[38:41]
	v_mfma_f32_16x16x32_bf16 v[38:41], v[150:153], v[196:199], v[38:41]
	v_mfma_f32_16x16x32_bf16 v[34:37], v[154:157], v[192:195], v[34:37]
	v_mfma_f32_16x16x32_bf16 v[34:37], v[158:161], v[196:199], v[34:37]
	v_mfma_f32_16x16x32_bf16 v[22:25], v[146:149], v[200:203], v[22:25]
	v_mfma_f32_16x16x32_bf16 v[22:25], v[150:153], v[204:207], v[22:25]
	v_mfma_f32_16x16x32_bf16 v[18:21], v[154:157], v[200:203], v[18:21]
	v_mfma_f32_16x16x32_bf16 v[18:21], v[158:161], v[204:207], v[18:21]
	v_mfma_f32_16x16x32_bf16 v[6:9], v[146:149], v[208:211], v[6:9]
	v_mfma_f32_16x16x32_bf16 v[6:9], v[150:153], v[212:215], v[6:9]
	v_mfma_f32_16x16x32_bf16 v[2:5], v[154:157], v[208:211], v[2:5]
	v_mfma_f32_16x16x32_bf16 v[2:5], v[158:161], v[212:215], v[2:5]
	v_mfma_f32_16x16x32_bf16 v[42:45], v[146:149], v[170:173], v[70:73]
	v_mfma_f32_16x16x32_bf16 v[42:45], v[150:153], v[188:191], v[42:45]
	s_setprio 2
	s_barrier
	v_mfma_f32_16x16x32_bf16 v[46:49], v[154:157], v[170:173], v[66:69]
	v_mfma_f32_16x16x32_bf16 v[46:49], v[158:161], v[188:191], v[46:49]
	s_setprio 0
	ds_read_b128 v[58:61], v184
	ds_read_b128 v[62:65], v184 offset:1024
	ds_read_b128 v[66:69], v184 offset:2048
	ds_read_b128 v[70:73], v184 offset:3072
	ds_read_b128 v[146:149], v185
	ds_read_b128 v[150:153], v185 offset:1024
	ds_read_b128 v[154:157], v185 offset:2048
	ds_read_b128 v[158:161], v185 offset:3072
	ds_read_b128 v[170:173], v183 offset:32768
	ds_read_b128 v[188:191], v183 offset:33792
	ds_read_b128 v[192:195], v183 offset:34816
	ds_read_b128 v[196:199], v183 offset:35840
	ds_read_b128 v[200:203], v183 offset:36864
	ds_read_b128 v[204:207], v183 offset:37888
	ds_read_b128 v[208:211], v183 offset:38912
	ds_read_b128 v[212:215], v183 offset:39936
	s_mov_b32 s82, m0
	s_mov_b32 m0, s48
	s_nop 0
	global_load_lds_dwordx4 v1, s[40:41]
	s_mov_b32 m0, s82
	s_nop 0
	s_mov_b32 s82, m0
	s_mov_b32 m0, s59
	s_nop 0
	global_load_lds_dwordx4 v177, s[40:41]
	s_mov_b32 m0, s82
	s_add_u32 s40, s40, 0x80000
	s_addc_u32 s41, s41, 0
	s_mov_b32 s82, m0
	s_mov_b32 m0, s62
	s_nop 0
	global_load_lds_dwordx4 v1, s[40:41]
	s_mov_b32 m0, s82
	s_nop 0
	s_mov_b32 s82, m0
	s_mov_b32 m0, s63
	s_nop 0
	global_load_lds_dwordx4 v177, s[40:41]
	s_mov_b32 m0, s82
	s_waitcnt vmcnt(8)
	s_waitcnt lgkmcnt(0)
	s_barrier
	s_setprio 1
	s_waitcnt lgkmcnt(7)
	v_mfma_f32_16x16x32_bf16 v[142:145], v[58:61], v[170:173], v[142:145]
	v_mfma_f32_16x16x32_bf16 v[142:145], v[62:65], v[188:191], v[142:145]
	s_waitcnt lgkmcnt(5)
	v_mfma_f32_16x16x32_bf16 v[138:141], v[66:69], v[170:173], v[138:141]
	v_mfma_f32_16x16x32_bf16 v[138:141], v[70:73], v[188:191], v[138:141]
	s_waitcnt lgkmcnt(3)
	v_mfma_f32_16x16x32_bf16 v[126:129], v[58:61], v[192:195], v[126:129]
	v_mfma_f32_16x16x32_bf16 v[126:129], v[62:65], v[196:199], v[126:129]
	s_waitcnt lgkmcnt(1)
	v_mfma_f32_16x16x32_bf16 v[122:125], v[66:69], v[192:195], v[122:125]
	v_mfma_f32_16x16x32_bf16 v[122:125], v[70:73], v[196:199], v[122:125]
	v_mfma_f32_16x16x32_bf16 v[110:113], v[58:61], v[200:203], v[110:113]
	v_mfma_f32_16x16x32_bf16 v[110:113], v[62:65], v[204:207], v[110:113]
	v_mfma_f32_16x16x32_bf16 v[106:109], v[66:69], v[200:203], v[106:109]
	v_mfma_f32_16x16x32_bf16 v[106:109], v[70:73], v[204:207], v[106:109]
	v_mfma_f32_16x16x32_bf16 v[94:97], v[58:61], v[208:211], v[94:97]
	v_mfma_f32_16x16x32_bf16 v[94:97], v[62:65], v[212:215], v[94:97]
	s_waitcnt lgkmcnt(0)
	v_mfma_f32_16x16x32_bf16 v[90:93], v[66:69], v[208:211], v[90:93]
	v_mfma_f32_16x16x32_bf16 v[90:93], v[70:73], v[212:215], v[90:93]
	s_setprio 0
	s_setprio 1
	v_mfma_f32_16x16x32_bf16 v[134:137], v[146:149], v[170:173], v[134:137]
	v_mfma_f32_16x16x32_bf16 v[134:137], v[150:153], v[188:191], v[134:137]
	v_mfma_f32_16x16x32_bf16 v[130:133], v[154:157], v[170:173], v[130:133]
	v_mfma_f32_16x16x32_bf16 v[130:133], v[158:161], v[188:191], v[130:133]
	v_mfma_f32_16x16x32_bf16 v[118:121], v[146:149], v[192:195], v[118:121]
	v_mfma_f32_16x16x32_bf16 v[118:121], v[150:153], v[196:199], v[118:121]
	v_mfma_f32_16x16x32_bf16 v[114:117], v[154:157], v[192:195], v[114:117]
	v_mfma_f32_16x16x32_bf16 v[114:117], v[158:161], v[196:199], v[114:117]
	v_mfma_f32_16x16x32_bf16 v[102:105], v[146:149], v[200:203], v[102:105]
	v_mfma_f32_16x16x32_bf16 v[102:105], v[150:153], v[204:207], v[102:105]
	v_mfma_f32_16x16x32_bf16 v[98:101], v[154:157], v[200:203], v[98:101]
	v_mfma_f32_16x16x32_bf16 v[98:101], v[158:161], v[204:207], v[98:101]
	v_mfma_f32_16x16x32_bf16 v[86:89], v[146:149], v[208:211], v[86:89]
	v_mfma_f32_16x16x32_bf16 v[86:89], v[150:153], v[212:215], v[86:89]
	s_setprio 2
	s_barrier
	v_mfma_f32_16x16x32_bf16 v[82:85], v[154:157], v[208:211], v[82:85]
	v_mfma_f32_16x16x32_bf16 v[82:85], v[158:161], v[212:215], v[82:85]
	s_setprio 0
	ds_read_b128 v[170:173], v183 offset:49152
	ds_read_b128 v[188:191], v183 offset:50176
	ds_read_b128 v[192:195], v183 offset:51200
	ds_read_b128 v[196:199], v183 offset:52224
	ds_read_b128 v[200:203], v183 offset:53248
	ds_read_b128 v[204:207], v183 offset:54272
	ds_read_b128 v[208:211], v183 offset:55296
	ds_read_b128 v[212:215], v183 offset:56320
	s_add_u32 s40, s36, 0x80
	s_addc_u32 s41, s37, 0
	s_mov_b32 s82, m0
	s_mov_b32 m0, s64
	s_nop 0
	global_load_lds_dwordx4 v176, s[40:41]
	s_mov_b32 m0, s82
	s_add_u32 s36, s36, 0x80080
	s_mov_b32 s82, m0
	s_mov_b32 m0, s65
	s_nop 0
	global_load_lds_dwordx4 v178, s[40:41]
	s_mov_b32 m0, s82
	s_addc_u32 s37, s37, 0
	s_mov_b32 s40, m0
	s_mov_b32 m0, s66
	s_nop 0
	global_load_lds_dwordx4 v176, s[36:37]
	s_mov_b32 m0, s40
	s_nop 0
	s_mov_b32 s40, m0
	s_mov_b32 m0, s67
	s_nop 0
	global_load_lds_dwordx4 v178, s[36:37]
	s_mov_b32 m0, s40
	s_waitcnt vmcnt(4)
	s_waitcnt lgkmcnt(0)
	s_barrier
	s_setprio 1
	s_waitcnt lgkmcnt(7)
	v_mfma_f32_16x16x32_bf16 v[78:81], v[58:61], v[170:173], v[78:81]
	v_mfma_f32_16x16x32_bf16 v[78:81], v[62:65], v[188:191], v[78:81]
	s_waitcnt lgkmcnt(5)
	v_mfma_f32_16x16x32_bf16 v[74:77], v[66:69], v[170:173], v[74:77]
	v_mfma_f32_16x16x32_bf16 v[74:77], v[70:73], v[188:191], v[74:77]
	s_waitcnt lgkmcnt(3)
	v_mfma_f32_16x16x32_bf16 v[54:57], v[58:61], v[192:195], v[54:57]
	v_mfma_f32_16x16x32_bf16 v[54:57], v[62:65], v[196:199], v[54:57]
	s_waitcnt lgkmcnt(1)
	v_mfma_f32_16x16x32_bf16 v[50:53], v[66:69], v[192:195], v[50:53]
	v_mfma_f32_16x16x32_bf16 v[50:53], v[70:73], v[196:199], v[50:53]
	v_mfma_f32_16x16x32_bf16 v[30:33], v[58:61], v[200:203], v[30:33]
	v_mfma_f32_16x16x32_bf16 v[30:33], v[62:65], v[204:207], v[30:33]
	v_mfma_f32_16x16x32_bf16 v[26:29], v[66:69], v[200:203], v[26:29]
	v_mfma_f32_16x16x32_bf16 v[26:29], v[70:73], v[204:207], v[26:29]
	v_mfma_f32_16x16x32_bf16 v[14:17], v[58:61], v[208:211], v[14:17]
	v_mfma_f32_16x16x32_bf16 v[14:17], v[62:65], v[212:215], v[14:17]
	s_waitcnt lgkmcnt(0)
	v_mfma_f32_16x16x32_bf16 v[10:13], v[66:69], v[208:211], v[10:13]
	v_mfma_f32_16x16x32_bf16 v[10:13], v[70:73], v[212:215], v[10:13]
	s_setprio 0
	s_setprio 1
	v_mfma_f32_16x16x32_bf16 v[42:45], v[146:149], v[170:173], v[42:45]
	v_mfma_f32_16x16x32_bf16 v[70:73], v[150:153], v[188:191], v[42:45]
	v_mfma_f32_16x16x32_bf16 v[42:45], v[154:157], v[170:173], v[46:49]
	v_mfma_f32_16x16x32_bf16 v[66:69], v[158:161], v[188:191], v[42:45]
	v_mfma_f32_16x16x32_bf16 v[38:41], v[146:149], v[192:195], v[38:41]
	v_mfma_f32_16x16x32_bf16 v[38:41], v[150:153], v[196:199], v[38:41]
	v_mfma_f32_16x16x32_bf16 v[34:37], v[154:157], v[192:195], v[34:37]
	v_mfma_f32_16x16x32_bf16 v[34:37], v[158:161], v[196:199], v[34:37]
	v_mfma_f32_16x16x32_bf16 v[22:25], v[146:149], v[200:203], v[22:25]
	v_mfma_f32_16x16x32_bf16 v[22:25], v[150:153], v[204:207], v[22:25]
	v_mfma_f32_16x16x32_bf16 v[18:21], v[154:157], v[200:203], v[18:21]
	v_mfma_f32_16x16x32_bf16 v[18:21], v[158:161], v[204:207], v[18:21]
	v_mfma_f32_16x16x32_bf16 v[6:9], v[146:149], v[208:211], v[6:9]
	v_mfma_f32_16x16x32_bf16 v[6:9], v[150:153], v[212:215], v[6:9]
	s_setprio 2
	s_barrier
	v_mfma_f32_16x16x32_bf16 v[2:5], v[154:157], v[208:211], v[2:5]
	v_mfma_f32_16x16x32_bf16 v[2:5], v[158:161], v[212:215], v[2:5]
	s_setprio 0
	s_add_i32 s81, s81, 2
	s_add_u32 s77, s77, 0x100
	s_addc_u32 s78, s78, 0
	s_add_u32 s34, s34, 0x100
	s_addc_u32 s35, s35, 0
	s_add_u32 s79, s79, 0x100
	s_addc_u32 s80, s80, 0
	s_cmp_gt_u32 s81, 29
	s_cbranch_scc0 .LBB0_2146
	s_and_b64 vcc, exec, s[14:15]
	s_cbranch_vccz .LBB0_2149
	s_barrier
